# pre-norm output (H) stored write-through (sc1) so the following barrier's L2 write-back has nothing to flush
# speedup vs baseline: 1.0078x; 1.0078x over previous
; __device__ __forceinline__ unsigned pk2(float lo, float hi) { unsigned r; asm("v_cvt_pk_bf16_f32 %0, %1, %2" : "=v"(r) : "v"(lo), "v"(hi)); return r; }
; __device__ __forceinline__ void p1_phase(const float* xin, const float* g, const float* modl, bf16* H, int wid, int lane) {
;     ...
;         for (int r = 0; r < 32; ++r) {
;             const float* xr = xin + (size_t)(base + r) * DM + 4 * lane;
;             f32x4 v[4]; float s = 0.f;
; #pragma unroll
;             for (int j = 0; j < 4; ++j) { v[j] = *(const f32x4*)(xr + 256 * j); s += (v[j][0] * v[j][0] + v[j][1] * v[j][1]) + (v[j][2] * v[j][2] + v[j][3] * v[j][3]); }
;             const float rs = __builtin_amdgcn_rsqf(wave_sum(s) * (1.0f / DM) + EPSN);
;             bf16* orow = H + (size_t)(base + r) * DM + 4 * lane;
; #pragma unroll
;             for (int j = 0; j < 4; ++j) { const f32x4 o = v[j] * rs * gs[j] + sh[j]; v2u w; w.x = pk2(o[0], o[1]); w.y = pk2(o[2], o[3]); *(v2u*)(orow + 256 * j) = w; }
;         }
.LBB0_82:
	v_lshl_add_u64 v[68:69], v[18:19], 0, s[12:13]
	global_load_dwordx4 v[52:55], v[68:69], off nt
	global_load_dwordx4 v[56:59], v[68:69], off offset:1024 nt
	global_load_dwordx4 v[60:63], v[68:69], off offset:2048 nt
	global_load_dwordx4 v[64:67], v[68:69], off offset:3072 nt
	s_add_u32 s12, s12, 0x1000
	s_addc_u32 s13, s13, 0
	s_cmp_eq_u32 s12, 0x20000
	s_waitcnt vmcnt(3)
	v_pk_mul_f32 v[68:69], v[54:55], v[54:55]
	v_pk_mul_f32 v[70:71], v[52:53], v[52:53]
	s_waitcnt vmcnt(2)
	v_pk_mul_f32 v[72:73], v[58:59], v[58:59]
	v_pk_mul_f32 v[74:75], v[56:57], v[56:57]
	v_pk_mov_b32 v[80:81], v[70:71], v[68:69] op_sel:[1,0]
	v_mov_b32_e32 v71, v69
	v_pk_mov_b32 v[68:69], v[74:75], v[72:73] op_sel:[1,0]
	v_mov_b32_e32 v75, v73
	s_waitcnt vmcnt(0)
	v_mul_f32_e32 v79, v65, v65
	v_mul_f32_e32 v76, v61, v61
	v_mul_f32_e32 v78, v63, v63
	v_pk_add_f32 v[70:71], v[80:81], v[70:71]
	v_pk_add_f32 v[68:69], v[68:69], v[74:75]
	v_mul_f32_e32 v51, v64, v64
	v_mul_f32_e32 v82, v66, v66
	v_mul_f32_e32 v83, v67, v67
	v_pk_fma_f32 v[72:73], v[60:61], v[60:61], v[76:77] op_sel_hi:[1,1,0]
	v_pk_fma_f32 v[76:77], v[62:63], v[62:63], v[78:79] op_sel_hi:[1,1,0]
	v_pk_add_f32 v[70:71], v[70:71], v[70:71] op_sel:[0,1] op_sel_hi:[1,0]
	v_pk_add_f32 v[68:69], v[68:69], v[68:69] op_sel:[0,1] op_sel_hi:[1,0]
	v_mov_b32_e32 v73, v82
	v_mov_b32_e32 v77, v83
	v_mov_b32_e32 v71, v51
	v_mov_b32_e32 v69, v79
	v_pk_add_f32 v[72:73], v[72:73], v[76:77]
	v_pk_add_f32 v[68:69], v[70:71], v[68:69]
	s_nop 0
	v_pk_add_f32 v[68:69], v[68:69], v[72:73]
	s_nop 0
	v_add_f32_e32 v51, v68, v69
	ds_bpermute_b32 v68, v40, v51
	s_waitcnt lgkmcnt(0)
	v_add_f32_e32 v51, v51, v68
	ds_bpermute_b32 v68, v41, v51
	s_waitcnt lgkmcnt(0)
	v_add_f32_e32 v51, v51, v68
	ds_bpermute_b32 v68, v42, v51
	s_waitcnt lgkmcnt(0)
	v_add_f32_e32 v51, v51, v68
	ds_bpermute_b32 v68, v43, v51
	s_waitcnt lgkmcnt(0)
	v_add_f32_e32 v51, v51, v68
	ds_bpermute_b32 v68, v44, v51
	s_waitcnt lgkmcnt(0)
	v_add_f32_e32 v51, v51, v68
	ds_bpermute_b32 v68, v45, v51
	s_waitcnt lgkmcnt(0)
	v_add_f32_e32 v51, v51, v68
	v_fmamk_f32 v51, v51, 0x3a800000, v50
	v_rsq_f32_e32 v68, v51
	s_nop 0
	v_pk_mul_f32 v[52:53], v[52:53], v[68:69] op_sel_hi:[1,0]
	v_pk_mul_f32 v[54:55], v[54:55], v[68:69] op_sel_hi:[1,0]
	v_pk_mul_f32 v[56:57], v[56:57], v[68:69] op_sel_hi:[1,0]
	v_pk_mul_f32 v[58:59], v[58:59], v[68:69] op_sel_hi:[1,0]
	v_pk_fma_f32 v[52:53], v[24:25], v[52:53], v[0:1]
	v_pk_mul_f32 v[60:61], v[60:61], v[68:69] op_sel_hi:[1,0]
	v_pk_mul_f32 v[62:63], v[62:63], v[68:69] op_sel_hi:[1,0]
	v_pk_mul_f32 v[64:65], v[64:65], v[68:69] op_sel_hi:[1,0]
	v_pk_mul_f32 v[66:67], v[66:67], v[68:69] op_sel_hi:[1,0]
	v_pk_fma_f32 v[54:55], v[22:23], v[54:55], v[2:3]
	v_pk_fma_f32 v[58:59], v[26:27], v[58:59], v[6:7]
	v_pk_fma_f32 v[56:57], v[28:29], v[56:57], v[4:5]
	v_cvt_pk_bf16_f32 v52, v52, v53
	v_cvt_pk_bf16_f32 v53, v54, v55
	v_pk_fma_f32 v[62:63], v[30:31], v[62:63], v[10:11]
	v_pk_fma_f32 v[60:61], v[32:33], v[60:61], v[8:9]
	v_pk_fma_f32 v[66:67], v[34:35], v[66:67], v[14:15]
	v_pk_fma_f32 v[64:65], v[36:37], v[64:65], v[12:13]
	v_cvt_pk_bf16_f32 v54, v56, v57
	v_cvt_pk_bf16_f32 v55, v58, v59
	v_cvt_pk_bf16_f32 v56, v60, v61
	v_cvt_pk_bf16_f32 v57, v62, v63
	v_cvt_pk_bf16_f32 v59, v66, v67
	s_nop 0
	v_cvt_pk_bf16_f32 v58, v64, v65
	global_store_dwordx2 v[38:39], v[52:53], off offset:-1024 sc1
	global_store_dwordx2 v[38:39], v[54:55], off offset:-512 sc1
	global_store_dwordx2 v[38:39], v[56:57], off sc1
	global_store_dwordx2 v[38:39], v[58:59], off offset:512 sc1
	v_lshl_add_u64 v[38:39], v[38:39], 0, s[10:11]
	s_cbranch_scc0 .LBB0_82
	s_add_i32 s0, s0, s4
	v_lshl_add_u64 v[18:19], v[18:19], 0, s[6:7]
	s_cmp_gt_i32 s0, 0xffff
	v_lshl_add_u64 v[20:21], v[20:21], 0, s[8:9]
	s_cbranch_scc0 .LBB0_81

; __device__ __forceinline__ unsigned pk2(float lo, float hi) { unsigned r; asm("v_cvt_pk_bf16_f32 %0, %1, %2" : "=v"(r) : "v"(lo), "v"(hi)); return r; }
; __device__ __forceinline__ void p1_phase(const float* xin, const float* g, const float* modl, bf16* H, int wid, int lane) {
;     ...
;         for (int r = 0; r < 32; ++r) {
;             const float* xr = xin + (size_t)(base + r) * DM + 4 * lane;
;             f32x4 v[4]; float s = 0.f;
; #pragma unroll
;             for (int j = 0; j < 4; ++j) { v[j] = *(const f32x4*)(xr + 256 * j); s += (v[j][0] * v[j][0] + v[j][1] * v[j][1]) + (v[j][2] * v[j][2] + v[j][3] * v[j][3]); }
;             const float rs = __builtin_amdgcn_rsqf(wave_sum(s) * (1.0f / DM) + EPSN);
;             bf16* orow = H + (size_t)(base + r) * DM + 4 * lane;
; #pragma unroll
;             for (int j = 0; j < 4; ++j) { const f32x4 o = v[j] * rs * gs[j] + sh[j]; v2u w; w.x = pk2(o[0], o[1]); w.y = pk2(o[2], o[3]); *(v2u*)(orow + 256 * j) = w; }
;         }
.LBB0_607:
	v_lshl_add_u64 v[74:75], v[24:25], 0, s[12:13]
	global_load_dwordx4 v[58:61], v[74:75], off nt
	global_load_dwordx4 v[62:65], v[74:75], off offset:1024 nt
	global_load_dwordx4 v[66:69], v[74:75], off offset:2048 nt
	global_load_dwordx4 v[70:73], v[74:75], off offset:3072 nt
	s_add_u32 s12, s12, 0x1000
	s_addc_u32 s13, s13, 0
	s_cmp_eq_u32 s12, 0x20000
	s_waitcnt vmcnt(3)
	v_pk_mul_f32 v[74:75], v[60:61], v[60:61]
	v_pk_mul_f32 v[76:77], v[58:59], v[58:59]
	s_waitcnt vmcnt(2)
	v_pk_mul_f32 v[78:79], v[64:65], v[64:65]
	v_pk_mul_f32 v[80:81], v[62:63], v[62:63]
	v_pk_mov_b32 v[86:87], v[76:77], v[74:75] op_sel:[1,0]
	v_mov_b32_e32 v77, v75
	v_pk_mov_b32 v[74:75], v[80:81], v[78:79] op_sel:[1,0]
	v_mov_b32_e32 v81, v79
	s_waitcnt vmcnt(0)
	v_mul_f32_e32 v85, v71, v71
	v_mul_f32_e32 v82, v67, v67
	v_mul_f32_e32 v84, v69, v69
	v_pk_add_f32 v[76:77], v[86:87], v[76:77]
	v_pk_add_f32 v[74:75], v[74:75], v[80:81]
	v_mul_f32_e32 v57, v70, v70
	v_mul_f32_e32 v88, v72, v72
	v_mul_f32_e32 v89, v73, v73
	v_pk_fma_f32 v[78:79], v[66:67], v[66:67], v[82:83] op_sel_hi:[1,1,0]
	v_pk_fma_f32 v[82:83], v[68:69], v[68:69], v[84:85] op_sel_hi:[1,1,0]
	v_pk_add_f32 v[76:77], v[76:77], v[76:77] op_sel:[0,1] op_sel_hi:[1,0]
	v_pk_add_f32 v[74:75], v[74:75], v[74:75] op_sel:[0,1] op_sel_hi:[1,0]
	v_mov_b32_e32 v79, v88
	v_mov_b32_e32 v83, v89
	v_mov_b32_e32 v77, v57
	v_mov_b32_e32 v75, v85
	v_pk_add_f32 v[78:79], v[78:79], v[82:83]
	v_pk_add_f32 v[74:75], v[76:77], v[74:75]
	s_nop 0
	v_pk_add_f32 v[74:75], v[74:75], v[78:79]
	s_nop 0
	v_add_f32_e32 v57, v74, v75
	ds_bpermute_b32 v74, v46, v57
	s_waitcnt lgkmcnt(0)
	v_add_f32_e32 v57, v57, v74
	ds_bpermute_b32 v74, v47, v57
	s_waitcnt lgkmcnt(0)
	v_add_f32_e32 v57, v57, v74
	ds_bpermute_b32 v74, v48, v57
	s_waitcnt lgkmcnt(0)
	v_add_f32_e32 v57, v57, v74
	ds_bpermute_b32 v74, v49, v57
	s_waitcnt lgkmcnt(0)
	v_add_f32_e32 v57, v57, v74
	ds_bpermute_b32 v74, v50, v57
	s_waitcnt lgkmcnt(0)
	v_add_f32_e32 v57, v57, v74
	ds_bpermute_b32 v74, v51, v57
	s_waitcnt lgkmcnt(0)
	v_add_f32_e32 v57, v57, v74
	v_fmamk_f32 v57, v57, 0x3a800000, v56
	v_rsq_f32_e32 v74, v57
	s_nop 0
	v_pk_mul_f32 v[58:59], v[58:59], v[74:75] op_sel_hi:[1,0]
	v_pk_mul_f32 v[60:61], v[60:61], v[74:75] op_sel_hi:[1,0]
	v_pk_mul_f32 v[62:63], v[62:63], v[74:75] op_sel_hi:[1,0]
	v_pk_mul_f32 v[64:65], v[64:65], v[74:75] op_sel_hi:[1,0]
	v_pk_fma_f32 v[58:59], v[30:31], v[58:59], v[0:1]
	v_pk_mul_f32 v[66:67], v[66:67], v[74:75] op_sel_hi:[1,0]
	v_pk_mul_f32 v[68:69], v[68:69], v[74:75] op_sel_hi:[1,0]
	v_pk_mul_f32 v[70:71], v[70:71], v[74:75] op_sel_hi:[1,0]
	v_pk_mul_f32 v[72:73], v[72:73], v[74:75] op_sel_hi:[1,0]
	v_pk_fma_f32 v[60:61], v[28:29], v[60:61], v[2:3]
	v_pk_fma_f32 v[64:65], v[32:33], v[64:65], v[6:7]
	v_pk_fma_f32 v[62:63], v[34:35], v[62:63], v[4:5]
	v_cvt_pk_bf16_f32 v58, v58, v59
	v_cvt_pk_bf16_f32 v59, v60, v61
	v_pk_fma_f32 v[68:69], v[36:37], v[68:69], v[10:11]
	v_pk_fma_f32 v[66:67], v[38:39], v[66:67], v[8:9]
	v_pk_fma_f32 v[72:73], v[40:41], v[72:73], v[14:15]
	v_pk_fma_f32 v[70:71], v[42:43], v[70:71], v[12:13]
	v_cvt_pk_bf16_f32 v60, v62, v63
	v_cvt_pk_bf16_f32 v61, v64, v65
	v_cvt_pk_bf16_f32 v62, v66, v67
	v_cvt_pk_bf16_f32 v63, v68, v69
	v_cvt_pk_bf16_f32 v65, v72, v73
	s_nop 0
	v_cvt_pk_bf16_f32 v64, v70, v71
	global_store_dwordx2 v[44:45], v[58:59], off offset:-1024 sc1
	global_store_dwordx2 v[44:45], v[60:61], off offset:-512 sc1
	global_store_dwordx2 v[44:45], v[62:63], off sc1
	global_store_dwordx2 v[44:45], v[64:65], off offset:512 sc1
	v_lshl_add_u64 v[44:45], v[44:45], 0, s[10:11]
	s_cbranch_scc0 .LBB0_607
	s_add_i32 s0, s0, s8
	v_lshl_add_u64 v[24:25], v[24:25], 0, s[4:5]
	s_cmp_gt_i32 s0, 0xffff
	v_lshl_add_u64 v[26:27], v[26:27], 0, s[6:7]
	s_cbranch_scc0 .LBB0_606
